# PREP memory rms-norm: the eight row loads issued together
# speedup vs baseline: 1.0019x; 1.0019x over previous
; DI unsigned pack2(float a, float b) { f2_t v = {a, b}; bf2_t r = __builtin_convertvector(v, bf2_t); return __builtin_bit_cast(unsigned, r); }
; DI float wave_sum(float v) { for (int o = 32; o > 0; o >>= 1) v += __shfl_xor(v, o); return v; }
; DI void rms_row_bf16(const float* __restrict__ src, const float* __restrict__ g, u16* __restrict__ dst, int lane) {
;   float4 v[4]; float ss = 0.f;
; #pragma unroll
;   for (int i = 0; i < 4; ++i) { v[i] = *(const float4*)(src + i * 256 + lane * 4); ss += v[i].x * v[i].x + v[i].y * v[i].y + v[i].z * v[i].z + v[i].w * v[i].w; }
;   ss = wave_sum(ss);
;   float rs = rsqrtf(ss * (1.f / 1024.f) + 1e-6f);
; #pragma unroll
;   for (int i = 0; i < 4; ++i) {
;     float4 gg = *(const float4*)(g + i * 256 + lane * 4);
;     uint2 o; o.x = pack2(v[i].x * rs * gg.x, v[i].y * rs * gg.y); o.y = pack2(v[i].z * rs * gg.z, v[i].w * rs * gg.w);
;     *(uint2*)(dst + i * 256 + lane * 4) = o;
;   }
; }
; DI void phase_prep(const Params& p, char* smem) {
;     ...
;   for (int row = bid * 4 + w; row < 4096; row += G * 4) {
;     int L = row >> 10, m = row & 1023;
;     rms_row_bf16(p.mem + (size_t)m * 1024, p.mem_norm_g + L * 1024, (u16*)(ws + OFF_MEMH) + (size_t)row * 1024, lane);
;   }
.LBB0_588:
	v_and_b32_e32 v16, 0xffc00, v15
	v_and_b32_e32 v6, 0xfffffc00, v8
	v_lshlrev_b32_e32 v198, 2, v16
	v_ashrrev_i32_e32 v7, 31, v6
	v_lshl_add_u64 v[40:41], v[2:3], 0, v[198:199]
	v_lshl_add_u64 v[6:7], v[6:7], 2, v[4:5]
	global_load_dwordx4 v[16:19], v[40:41], off
	global_load_dwordx4 v[24:27], v[40:41], off offset:1024
	global_load_dwordx4 v[32:35], v[40:41], off offset:2048
	global_load_dwordx4 v[20:23], v[6:7], off
	global_load_dwordx4 v[28:31], v[6:7], off offset:1024
	global_load_dwordx4 v[36:39], v[6:7], off offset:2048
	global_load_dwordx4 v[44:47], v[6:7], off offset:3072
	global_load_dwordx4 v[40:43], v[40:41], off offset:3072
	s_waitcnt lgkmcnt(0)
	v_add_u32_e32 v8, s26, v8
	v_add_u32_e32 v15, s8, v15
	s_waitcnt vmcnt(7)
	v_pk_mul_f32 v[48:49], v[16:17], v[16:17]
	v_pk_mul_f32 v[50:51], v[18:19], v[18:19]
	s_waitcnt vmcnt(6)
	v_pk_fma_f32 v[48:49], v[24:25], v[24:25], v[48:49]
	v_pk_fma_f32 v[50:51], v[26:27], v[26:27], v[50:51]
	s_waitcnt vmcnt(5)
	v_pk_fma_f32 v[48:49], v[32:33], v[32:33], v[48:49]
	v_pk_fma_f32 v[50:51], v[34:35], v[34:35], v[50:51]
	s_waitcnt vmcnt(0)
	v_pk_fma_f32 v[48:49], v[40:41], v[40:41], v[48:49]
	v_pk_fma_f32 v[50:51], v[42:43], v[42:43], v[50:51]
	s_nop 0
	v_pk_add_f32 v[48:49], v[48:49], v[50:51]
	s_nop 0
	v_add_f32_e32 v6, v48, v49
	ds_bpermute_b32 v7, v9, v6
	s_waitcnt lgkmcnt(0)
	v_add_f32_e32 v6, v6, v7
	ds_bpermute_b32 v7, v10, v6
	s_waitcnt lgkmcnt(0)
	v_add_f32_e32 v6, v6, v7
	ds_bpermute_b32 v7, v11, v6
	s_waitcnt lgkmcnt(0)
	v_add_f32_e32 v6, v6, v7
	ds_bpermute_b32 v7, v12, v6
	s_waitcnt lgkmcnt(0)
	v_add_f32_e32 v6, v6, v7
	ds_bpermute_b32 v7, v13, v6
	s_waitcnt lgkmcnt(0)
	v_add_f32_e32 v6, v6, v7
	ds_bpermute_b32 v7, v14, v6
	s_waitcnt lgkmcnt(0)
	v_add_f32_e32 v6, v6, v7
	v_fmamk_f32 v6, v6, 0x3a800000, v206
	v_cmp_gt_f32_e32 vcc, s9, v6
	v_mul_f32_e32 v7, 0x4b800000, v6
	s_nop 0
	v_cndmask_b32_e32 v6, v6, v7, vcc
	v_rsq_f32_e32 v6, v6
	s_nop 0
	v_mul_f32_e32 v7, 0x45800000, v6
	v_cndmask_b32_e32 v6, v6, v7, vcc
	v_pk_mul_f32 v[16:17], v[16:17], v[6:7] op_sel_hi:[1,0]
	v_pk_mul_f32 v[18:19], v[18:19], v[6:7] op_sel_hi:[1,0]
	v_pk_mul_f32 v[16:17], v[20:21], v[16:17]
	v_pk_mul_f32 v[18:19], v[22:23], v[18:19]
	v_cvt_pk_bf16_f32 v16, v16, v17
	v_cvt_pk_bf16_f32 v17, v18, v19
	global_store_dwordx2 v[0:1], v[16:17], off offset:-1024
	v_pk_mul_f32 v[16:17], v[24:25], v[6:7] op_sel_hi:[1,0]
	v_pk_mul_f32 v[18:19], v[26:27], v[6:7] op_sel_hi:[1,0]
	v_pk_mul_f32 v[16:17], v[28:29], v[16:17]
	v_pk_mul_f32 v[18:19], v[30:31], v[18:19]
	v_cvt_pk_bf16_f32 v16, v16, v17
	v_cvt_pk_bf16_f32 v17, v18, v19
	global_store_dwordx2 v[0:1], v[16:17], off offset:-512
	v_pk_mul_f32 v[16:17], v[32:33], v[6:7] op_sel_hi:[1,0]
	v_pk_mul_f32 v[18:19], v[34:35], v[6:7] op_sel_hi:[1,0]
	v_pk_mul_f32 v[16:17], v[16:17], v[36:37]
	v_pk_mul_f32 v[18:19], v[18:19], v[38:39]
	v_cvt_pk_bf16_f32 v16, v16, v17
	v_cvt_pk_bf16_f32 v17, v18, v19
	global_store_dwordx2 v[0:1], v[16:17], off
	v_pk_mul_f32 v[16:17], v[40:41], v[6:7] op_sel_hi:[1,0]
	v_pk_mul_f32 v[6:7], v[42:43], v[6:7] op_sel_hi:[1,0]
	s_waitcnt vmcnt(3)
	v_pk_mul_f32 v[16:17], v[16:17], v[44:45]
	v_pk_mul_f32 v[6:7], v[6:7], v[46:47]
	v_cvt_pk_bf16_f32 v16, v16, v17
	v_cvt_pk_bf16_f32 v17, v6, v7
	v_cmp_lt_i32_e32 vcc, s69, v8
	global_store_dwordx2 v[0:1], v[16:17], off offset:512
	v_lshl_add_u64 v[0:1], v[0:1], 0, s[10:11]
	s_or_b64 s[6:7], vcc, s[6:7]
	s_andn2_b64 exec, exec, s[6:7]
	s_cbranch_execnz .LBB0_588
